# weight prep spread into idle tails: layer-0 FFN weights converted by idle workgroups of the w_in GEMM last round; layer-1 weights converted during layer-0 tails and layer-1 w_in GEMM last round
# speedup vs baseline: 1.0193x; 1.0125x over previous
.LBB0_115:
	s_or_b64 exec, exec, s[2:3]
	s_abs_i32 s15, s12
	v_cvt_f32_u32_e32 v2, s15
	v_lshlrev_b32_e32 v0, 2, v76
	v_and_b32_e32 v82, 60, v0
	s_sub_i32 s2, 0, s15
	v_rcp_iflag_f32_e32 v0, v2
	s_mov_b32 s13, s88
	s_add_i32 s14, s13, s12
	v_mul_f32_e32 v0, 0x4f7ffffe, v0
	v_cvt_u32_f32_e32 v0, v0
	s_abs_i32 s1, s14
	s_ashr_i32 s0, s14, 31
	v_ashrrev_i32_e32 v78, 3, v76
	v_readfirstlane_b32 s16, v0
	s_mul_i32 s2, s2, s16
	s_mul_hi_u32 s2, s16, s2
	s_add_i32 s16, s16, s2
	s_mul_hi_u32 s2, s1, s16
	s_mul_i32 s2, s2, s15
	s_sub_i32 s1, s1, s2
	s_sub_i32 s2, s1, s15
	s_cmp_ge_u32 s1, s15
	s_cselect_b32 s1, s2, s1
	s_sub_i32 s2, s1, s15
	s_cmp_ge_u32 s1, s15
	s_cselect_b32 s1, s2, s1
	s_xor_b32 s1, s1, s0
	v_lshlrev_b32_e32 v2, 3, v76
	s_sub_i32 s17, s1, s0
	v_ashrrev_i32_e32 v77, 4, v76
	v_mov_b32_e32 v1, 0
	v_lshl_add_u32 v79, v82, 2, 0
	v_and_b32_e32 v80, 56, v2
	s_cmpk_lt_i32 s17, 0x480
	v_lshl_add_u32 v81, v78, 2, 0
	s_load_dword s59, s[90:91], 0xd8
	v_mbcnt_lo_u32_b32 v100, -1, 0
	v_mbcnt_hi_u32_b32 v100, -1, v100
	s_lshr_b32 s69, s94, 6
	s_lshl_b32 s82, s69, 10
	s_lshl_b32 s83, s69, 1
	s_lshr_b32 s98, s69, 2
	v_lshrrev_b32_e32 v101, 5, v100
	v_and_b32_e32 v113, 31, v100
	s_add_i32 s70, s83, 0
	v_add_u32_e32 v102, s70, v101
	s_add_i32 s70, s98, 0
	v_xor_b32_e32 v106, s70, v113
	v_lshlrev_b32_e32 v106, 4, v106
	s_add_i32 s70, s83, 16
	v_add_u32_e32 v103, s70, v101
	s_add_i32 s70, s98, 2
	v_xor_b32_e32 v107, s70, v113
	v_lshlrev_b32_e32 v107, 4, v107
	s_add_i32 s70, s83, 32
	v_add_u32_e32 v104, s70, v101
	s_add_i32 s70, s98, 4
	v_xor_b32_e32 v108, s70, v113
	v_lshlrev_b32_e32 v108, 4, v108
	s_add_i32 s70, s83, 48
	v_add_u32_e32 v105, s70, v101
	s_add_i32 s70, s98, 6
	v_xor_b32_e32 v109, s70, v113
	v_lshlrev_b32_e32 v109, 4, v109
	s_lshr_b32 s70, s94, 3
	v_lshrrev_b32_e32 v112, 3, v100
	v_add_u32_e32 v112, s70, v112
	v_and_b32_e32 v101, 7, v100
	v_lshlrev_b32_e32 v111, 4, v101
	v_lshrrev_b32_e32 v113, 2, v112
	v_xor_b32_e32 v113, v113, v101
	v_lshlrev_b32_e32 v113, 4, v113
	v_lshl_add_u32 v110, v101, 12, v113
	v_and_b32_e32 v113, 3, v112
	v_lshl_add_u32 v110, v113, 2, v110
	s_waitcnt lgkmcnt(0)
	s_add_u32 s61, s88, 0
	s_mov_b32 s60, s61
	s_mov_b32 s101, 5280
	s_mov_b32 s58, -2

.LBB0_290:
	s_barrier
	s_cmp_lt_u32 s88, 200
	s_cbranch_scc1 .Lwph2_skip
	s_load_dword s59, s[90:91], 0xd8
	v_mbcnt_lo_u32_b32 v100, -1, 0
	v_mbcnt_hi_u32_b32 v100, -1, v100
	s_lshr_b32 s69, s94, 6
	s_lshl_b32 s82, s69, 10
	s_lshl_b32 s83, s69, 1
	s_lshr_b32 s98, s69, 2
	v_lshrrev_b32_e32 v101, 5, v100
	v_and_b32_e32 v113, 31, v100
	s_add_i32 s70, s83, 0
	v_add_u32_e32 v102, s70, v101
	s_add_i32 s70, s98, 0
	v_xor_b32_e32 v106, s70, v113
	v_lshlrev_b32_e32 v106, 4, v106
	s_add_i32 s70, s83, 16
	v_add_u32_e32 v103, s70, v101
	s_add_i32 s70, s98, 2
	v_xor_b32_e32 v107, s70, v113
	v_lshlrev_b32_e32 v107, 4, v107
	s_add_i32 s70, s83, 32
	v_add_u32_e32 v104, s70, v101
	s_add_i32 s70, s98, 4
	v_xor_b32_e32 v108, s70, v113
	v_lshlrev_b32_e32 v108, 4, v108
	s_add_i32 s70, s83, 48
	v_add_u32_e32 v105, s70, v101
	s_add_i32 s70, s98, 6
	v_xor_b32_e32 v109, s70, v113
	v_lshlrev_b32_e32 v109, 4, v109
	s_lshr_b32 s70, s94, 3
	v_lshrrev_b32_e32 v112, 3, v100
	v_add_u32_e32 v112, s70, v112
	v_and_b32_e32 v101, 7, v100
	v_lshlrev_b32_e32 v111, 4, v101
	v_lshrrev_b32_e32 v113, 2, v112
	v_xor_b32_e32 v113, v113, v101
	v_lshlrev_b32_e32 v113, 4, v113
	v_lshl_add_u32 v110, v101, 12, v113
	v_and_b32_e32 v113, 3, v112
	v_lshl_add_u32 v110, v113, 2, v110
	s_waitcnt lgkmcnt(0)
	s_sub_u32 s61, s88, 200
	s_add_u32 s61, s61, 5280
	s_mov_b32 s59, 56
	s_mov_b32 s101, 7520
	s_mov_b32 s60, s61
	s_mov_b32 s58, -2

.Lwph2_skip:
.LBB0_291:
	s_cmp_lt_i32 s92, 4
	s_cselect_b64 s[2:3], -1, 0
	s_cmp_gt_i32 s92, 3
	s_cselect_b64 s[0:1], -1, 0
	s_cmp_lt_i32 s93, 4
	s_cselect_b64 s[6:7], -1, 0
	s_or_b64 s[0:1], s[0:1], s[6:7]
	s_and_b64 vcc, exec, s[0:1]
	s_cbranch_vccnz .LBB0_391
	s_andn2_b64 vcc, exec, s[4:5]
	s_cbranch_vccnz .LBB0_303
	s_waitcnt vmcnt(0)
	v_readlane_b32 s0, v245, 32
	v_readlane_b32 s1, v245, 33
	s_add_i32 s95, s95, 1
	s_andn2_b64 vcc, exec, s[0:1]
	s_waitcnt lgkmcnt(0)
	s_barrier
	s_cbranch_vccnz .LBB0_302
	v_mbcnt_lo_u32_b32 v0, -1, 0
	v_mbcnt_hi_u32_b32 v0, -1, v0
	v_cmp_eq_u32_e32 vcc, 0, v0
	s_and_saveexec_b64 s[4:5], vcc
	s_cbranch_execz .LBB0_301
	v_readlane_b32 s0, v245, 50
	s_lshl_b32 s0, s0, 8
	s_add_u32 s0, s96, s0
	s_addc_u32 s1, s97, 0
	v_mov_b32_e32 v0, 0x1000
	v_mov_b32_e32 v1, 1
	global_atomic_add v0, v0, v1, s[0:1] sc0
	v_readlane_b32 s0, v245, 51
	s_add_u32 s6, s86, 0x4b500
	s_mul_i32 s0, s95, s0
	s_addc_u32 s7, s87, 0
	s_waitcnt vmcnt(0)
	v_add_u32_e32 v0, 1, v0
	v_cmp_eq_u32_e32 vcc, s0, v0
	s_and_saveexec_b64 s[8:9], vcc
	s_cbranch_execz .LBB0_298
	s_mov_b64 s[10:11], exec
	v_mbcnt_lo_u32_b32 v0, s10, 0
	buffer_wbl2 sc1
	s_waitcnt vmcnt(0)
	v_mbcnt_hi_u32_b32 v0, s11, v0
	v_cmp_eq_u32_e32 vcc, 0, v0
	s_and_b64 s[0:1], exec, vcc
	s_mov_b64 exec, s[0:1]
	s_cbranch_execz .LBB0_298
	s_bcnt1_i32_b64 s0, s[10:11]
	v_mov_b32_e32 v0, 0
	v_mov_b32_e32 v1, s0
	global_atomic_add v0, v1, s[6:7]

.LBB0_710:
	s_barrier
	s_cmp_lt_u32 s88, 216
	s_cbranch_scc1 .Lwph9_skip
	s_load_dword s59, s[90:91], 0xd8
	v_mbcnt_lo_u32_b32 v100, -1, 0
	v_mbcnt_hi_u32_b32 v100, -1, v100
	s_lshr_b32 s69, s94, 6
	s_lshl_b32 s82, s69, 10
	s_lshl_b32 s83, s69, 1
	s_lshr_b32 s98, s69, 2
	v_lshrrev_b32_e32 v101, 5, v100
	v_and_b32_e32 v113, 31, v100
	s_add_i32 s70, s83, 0
	v_add_u32_e32 v102, s70, v101
	s_add_i32 s70, s98, 0
	v_xor_b32_e32 v106, s70, v113
	v_lshlrev_b32_e32 v106, 4, v106
	s_add_i32 s70, s83, 16
	v_add_u32_e32 v103, s70, v101
	s_add_i32 s70, s98, 2
	v_xor_b32_e32 v107, s70, v113
	v_lshlrev_b32_e32 v107, 4, v107
	s_add_i32 s70, s83, 32
	v_add_u32_e32 v104, s70, v101
	s_add_i32 s70, s98, 4
	v_xor_b32_e32 v108, s70, v113
	v_lshlrev_b32_e32 v108, 4, v108
	s_add_i32 s70, s83, 48
	v_add_u32_e32 v105, s70, v101
	s_add_i32 s70, s98, 6
	v_xor_b32_e32 v109, s70, v113
	v_lshlrev_b32_e32 v109, 4, v109
	s_lshr_b32 s70, s94, 3
	v_lshrrev_b32_e32 v112, 3, v100
	v_add_u32_e32 v112, s70, v112
	v_and_b32_e32 v101, 7, v100
	v_lshlrev_b32_e32 v111, 4, v101
	v_lshrrev_b32_e32 v113, 2, v112
	v_xor_b32_e32 v113, v113, v101
	v_lshlrev_b32_e32 v113, 4, v113
	v_lshl_add_u32 v110, v101, 12, v113
	v_and_b32_e32 v113, 3, v112
	v_lshl_add_u32 v110, v113, 2, v110
	s_waitcnt lgkmcnt(0)
	s_sub_u32 s61, s88, 216
	s_add_u32 s61, s61, 768
	s_mov_b32 s59, 40
	s_mov_b32 s101, 2368
	s_mov_b32 s60, s61
	s_mov_b32 s58, -2

.LBB0_771:
	s_barrier
	s_cmp_lt_u32 s88, 176
	s_cbranch_scc1 .Lwph10_skip
	s_load_dword s59, s[90:91], 0xd8
	v_mbcnt_lo_u32_b32 v100, -1, 0
	v_mbcnt_hi_u32_b32 v100, -1, v100
	s_lshr_b32 s69, s94, 6
	s_lshl_b32 s82, s69, 10
	s_lshl_b32 s83, s69, 1
	s_lshr_b32 s98, s69, 2
	v_lshrrev_b32_e32 v101, 5, v100
	v_and_b32_e32 v113, 31, v100
	s_add_i32 s70, s83, 0
	v_add_u32_e32 v102, s70, v101
	s_add_i32 s70, s98, 0
	v_xor_b32_e32 v106, s70, v113
	v_lshlrev_b32_e32 v106, 4, v106
	s_add_i32 s70, s83, 16
	v_add_u32_e32 v103, s70, v101
	s_add_i32 s70, s98, 2
	v_xor_b32_e32 v107, s70, v113
	v_lshlrev_b32_e32 v107, 4, v107
	s_add_i32 s70, s83, 32
	v_add_u32_e32 v104, s70, v101
	s_add_i32 s70, s98, 4
	v_xor_b32_e32 v108, s70, v113
	v_lshlrev_b32_e32 v108, 4, v108
	s_add_i32 s70, s83, 48
	v_add_u32_e32 v105, s70, v101
	s_add_i32 s70, s98, 6
	v_xor_b32_e32 v109, s70, v113
	v_lshlrev_b32_e32 v109, 4, v109
	s_lshr_b32 s70, s94, 3
	v_lshrrev_b32_e32 v112, 3, v100
	v_add_u32_e32 v112, s70, v112
	v_and_b32_e32 v101, 7, v100
	v_lshlrev_b32_e32 v111, 4, v101
	v_lshrrev_b32_e32 v113, 2, v112
	v_xor_b32_e32 v113, v113, v101
	v_lshlrev_b32_e32 v113, 4, v113
	v_lshl_add_u32 v110, v101, 12, v113
	v_and_b32_e32 v113, 3, v112
	v_lshl_add_u32 v110, v113, 2, v110
	s_waitcnt lgkmcnt(0)
	s_sub_u32 s61, s88, 176
	s_add_u32 s61, s61, 2368
	s_mov_b32 s59, 80
	s_mov_b32 s101, 3008
	s_mov_b32 s60, s61
	s_mov_b32 s58, -2

.LBB0_784:
	s_mov_b64 s[4:5], 0
	s_load_dword s12, s[90:91], 0xd8
	v_mbcnt_lo_u32_b32 v0, -1, 0
	v_mbcnt_hi_u32_b32 v77, -1, v0
	v_or_b32_e32 v76, s94, v77
	s_mov_b32 s0, s88
	s_add_u32 s8, s86, s4
	s_waitcnt lgkmcnt(0)
	s_mov_b32 s1, s12
	v_mov_b32_e32 v78, v76
	s_mov_b32 s13, s12
	s_addc_u32 s9, s87, s5
	s_abs_i32 s22, s13
	v_cvt_f32_u32_e32 v2, s22
	v_lshlrev_b32_e32 v0, 2, v78
	v_and_b32_e32 v84, 60, v0
	s_sub_i32 s2, 0, s22
	v_rcp_iflag_f32_e32 v0, v2
	s_mov_b32 s14, s88
	s_add_i32 s15, s14, s13
	v_mul_f32_e32 v0, 0x4f7ffffe, v0
	v_cvt_u32_f32_e32 v0, v0
	s_abs_i32 s1, s15
	s_ashr_i32 s0, s15, 31
	v_ashrrev_i32_e32 v80, 3, v78
	v_readfirstlane_b32 s23, v0
	s_mul_i32 s2, s2, s23
	s_mul_hi_u32 s2, s23, s2
	s_add_i32 s23, s23, s2
	s_mul_hi_u32 s2, s1, s23
	s_mul_i32 s2, s2, s22
	s_sub_i32 s1, s1, s2
	s_sub_i32 s2, s1, s22
	s_cmp_ge_u32 s1, s22
	s_cselect_b32 s1, s2, s1
	s_sub_i32 s2, s1, s22
	s_cmp_ge_u32 s1, s22
	s_cselect_b32 s1, s2, s1
	s_xor_b32 s1, s1, s0
	v_lshlrev_b32_e32 v2, 3, v78
	s_sub_i32 s24, s1, s0
	v_ashrrev_i32_e32 v79, 4, v78
	v_mov_b32_e32 v1, 0
	v_lshl_add_u32 v81, v84, 2, 0
	v_and_b32_e32 v82, 56, v2
	s_cmpk_lt_i32 s24, 0x480
	v_lshl_add_u32 v83, v80, 2, 0
	s_load_dword s59, s[90:91], 0xd8
	v_mbcnt_lo_u32_b32 v100, -1, 0
	v_mbcnt_hi_u32_b32 v100, -1, v100
	s_lshr_b32 s69, s94, 6
	s_lshl_b32 s82, s69, 10
	s_lshl_b32 s83, s69, 1
	s_lshr_b32 s98, s69, 2
	v_lshrrev_b32_e32 v101, 5, v100
	v_and_b32_e32 v113, 31, v100
	s_add_i32 s70, s83, 0
	v_add_u32_e32 v102, s70, v101
	s_add_i32 s70, s98, 0
	v_xor_b32_e32 v106, s70, v113
	v_lshlrev_b32_e32 v106, 4, v106
	s_add_i32 s70, s83, 16
	v_add_u32_e32 v103, s70, v101
	s_add_i32 s70, s98, 2
	v_xor_b32_e32 v107, s70, v113
	v_lshlrev_b32_e32 v107, 4, v107
	s_add_i32 s70, s83, 32
	v_add_u32_e32 v104, s70, v101
	s_add_i32 s70, s98, 4
	v_xor_b32_e32 v108, s70, v113
	v_lshlrev_b32_e32 v108, 4, v108
	s_add_i32 s70, s83, 48
	v_add_u32_e32 v105, s70, v101
	s_add_i32 s70, s98, 6
	v_xor_b32_e32 v109, s70, v113
	v_lshlrev_b32_e32 v109, 4, v109
	s_lshr_b32 s70, s94, 3
	v_lshrrev_b32_e32 v112, 3, v100
	v_add_u32_e32 v112, s70, v112
	v_and_b32_e32 v101, 7, v100
	v_lshlrev_b32_e32 v111, 4, v101
	v_lshrrev_b32_e32 v113, 2, v112
	v_xor_b32_e32 v113, v113, v101
	v_lshlrev_b32_e32 v113, 4, v113
	v_lshl_add_u32 v110, v101, 12, v113
	v_and_b32_e32 v113, 3, v112
	v_lshl_add_u32 v110, v113, 2, v110
	s_waitcnt lgkmcnt(0)
	s_add_u32 s61, s88, 3008
	s_mov_b32 s60, s61
	s_mov_b32 s101, 3304
	s_mov_b32 s58, -2

.LBB0_966:
	s_barrier
	s_cmp_lt_u32 s88, 132
	s_cbranch_scc1 .Lwph12_skip
	s_load_dword s59, s[90:91], 0xd8
	v_mbcnt_lo_u32_b32 v100, -1, 0
	v_mbcnt_hi_u32_b32 v100, -1, v100
	s_lshr_b32 s69, s94, 6
	s_lshl_b32 s82, s69, 10
	s_lshl_b32 s83, s69, 1
	s_lshr_b32 s98, s69, 2
	v_lshrrev_b32_e32 v101, 5, v100
	v_and_b32_e32 v113, 31, v100
	s_add_i32 s70, s83, 0
	v_add_u32_e32 v102, s70, v101
	s_add_i32 s70, s98, 0
	v_xor_b32_e32 v106, s70, v113
	v_lshlrev_b32_e32 v106, 4, v106
	s_add_i32 s70, s83, 16
	v_add_u32_e32 v103, s70, v101
	s_add_i32 s70, s98, 2
	v_xor_b32_e32 v107, s70, v113
	v_lshlrev_b32_e32 v107, 4, v107
	s_add_i32 s70, s83, 32
	v_add_u32_e32 v104, s70, v101
	s_add_i32 s70, s98, 4
	v_xor_b32_e32 v108, s70, v113
	v_lshlrev_b32_e32 v108, 4, v108
	s_add_i32 s70, s83, 48
	v_add_u32_e32 v105, s70, v101
	s_add_i32 s70, s98, 6
	v_xor_b32_e32 v109, s70, v113
	v_lshlrev_b32_e32 v109, 4, v109
	s_lshr_b32 s70, s94, 3
	v_lshrrev_b32_e32 v112, 3, v100
	v_add_u32_e32 v112, s70, v112
	v_and_b32_e32 v101, 7, v100
	v_lshlrev_b32_e32 v111, 4, v101
	v_lshrrev_b32_e32 v113, 2, v112
	v_xor_b32_e32 v113, v113, v101
	v_lshlrev_b32_e32 v113, 4, v113
	v_lshl_add_u32 v110, v101, 12, v113
	v_and_b32_e32 v113, 3, v112
	v_lshl_add_u32 v110, v113, 2, v110
	s_waitcnt lgkmcnt(0)
	s_sub_u32 s61, s88, 132
	s_add_u32 s61, s61, 3304
	s_mov_b32 s59, 124
	s_mov_b32 s101, 7520
	s_mov_b32 s60, s61
	s_mov_b32 s58, -2

.Lwph12_skip:
.LBB0_967:
	s_cmp_lt_i32 s92, 14
	s_cselect_b64 s[2:3], -1, 0
	s_cmp_gt_i32 s92, 13
	s_cselect_b64 s[0:1], -1, 0
	s_cmp_lt_i32 s93, 14
	s_cselect_b64 s[6:7], -1, 0
	s_or_b64 s[0:1], s[0:1], s[6:7]
	s_and_b64 vcc, exec, s[0:1]
	s_cbranch_vccnz .LBB0_1039
	s_andn2_b64 vcc, exec, s[4:5]
	s_cbranch_vccnz .LBB0_979
	s_waitcnt vmcnt(0)
	v_readlane_b32 s0, v245, 32
	v_readlane_b32 s1, v245, 33
	s_add_i32 s95, s95, 1
	s_andn2_b64 vcc, exec, s[0:1]
	s_waitcnt vmcnt(0) lgkmcnt(0)
	s_barrier
	s_cbranch_vccnz .LBB0_978
	v_mbcnt_lo_u32_b32 v0, -1, 0
	v_mbcnt_hi_u32_b32 v0, -1, v0
	v_cmp_eq_u32_e32 vcc, 0, v0
	s_and_saveexec_b64 s[4:5], vcc
	s_cbranch_execz .LBB0_977
	v_readlane_b32 s0, v245, 50
	s_lshl_b32 s0, s0, 8
	s_add_u32 s0, s96, s0
	s_addc_u32 s1, s97, 0
	v_mov_b32_e32 v0, 0x1000
	v_mov_b32_e32 v1, 1
	global_atomic_add v0, v0, v1, s[0:1] sc0
	v_readlane_b32 s0, v245, 51
	s_add_u32 s6, s86, 0x4b500
	s_mul_i32 s0, s95, s0
	s_addc_u32 s7, s87, 0
	s_waitcnt vmcnt(0)
	v_add_u32_e32 v0, 1, v0
	v_cmp_eq_u32_e32 vcc, s0, v0
	s_and_saveexec_b64 s[8:9], vcc
	s_cbranch_execz .LBB0_974
	s_mov_b64 s[10:11], exec
	v_mbcnt_lo_u32_b32 v0, s10, 0
	buffer_wbl2 sc1
	s_waitcnt vmcnt(0)
	v_mbcnt_hi_u32_b32 v0, s11, v0
	v_cmp_eq_u32_e32 vcc, 0, v0
	s_and_b64 s[0:1], exec, vcc
	s_mov_b64 exec, s[0:1]
	s_cbranch_execz .LBB0_974
	s_bcnt1_i32_b64 s0, s[10:11]
	v_mov_b32_e32 v0, 0
	v_mov_b32_e32 v1, s0
	global_atomic_add v0, v1, s[6:7]
